# diff-attn: hand-written fast tile iteration (far/unmasked case) + v_max3 + global pos load
# speedup vs baseline: 1.0018x; 1.0018x over previous
; #define DF_GLOAD(k0) do { k0r = ldg<u32x4>(QK + (size_t)((k0) + kr0) * 1024 + 512 + hd * 128 + kc0 * 8); k1r = ldg<u32x4>(QK + (size_t)((k0) + kr1) * 1024 + 512 + hd * 128 + kc0 * 8); \
;         v0r = ldg<u32x4>(Vp + (size_t)vr0 * S + (k0) + vc0 * 8); v1r = ldg<u32x4>(Vp + (size_t)vr1 * S + (k0) + vc0 * 8); if (tid < 64) pkr = pos[(k0) + tid]; } while (0)
; __device__ __forceinline__ void diff_unit(LAS unsigned char* lds, const AP a, int l, int grp, int bl, int hd, int qb) {
;     ...
;         if (kt + 2 < ntiles) DF_GLOAD(k0 + 128);
.LBB0_151:
	v_add_u32_e32 v5, s12, v218
	v_add_u32_e32 v0, 0x80, v5
	v_lshlrev_b64 v[2:3], 11, v[0:1]
	v_add_u32_e32 v0, 0xa0, v5
	v_lshl_add_u64 v[2:3], v[190:191], 0, v[2:3]
	v_lshlrev_b64 v[6:7], 11, v[0:1]
	s_lshl_b64 s[0:1], s[12:13], 1
	v_lshl_add_u64 v[6:7], v[190:191], 0, v[6:7]
	global_load_dwordx4 v[162:165], v[2:3], off offset:1024
	global_load_dwordx4 v[166:169], v[6:7], off offset:1024
	v_lshl_add_u64 v[2:3], v[186:187], 0, s[0:1]
	v_lshl_add_u64 v[6:7], v[188:189], 0, s[0:1]
	global_load_dwordx4 v[170:173], v[2:3], off offset:256
	global_load_dwordx4 v[174:177], v[6:7], off offset:256
	s_and_saveexec_b64 s[0:1], s[30:31]
	s_cbranch_execz .LBB0_153
	v_readlane_b32 s2, v255, 34
	v_add_u32_e32 v0, s12, v182
	v_readlane_b32 s3, v255, 35
	s_nop 1
	v_lshl_add_u64 v[2:3], v[0:1], 2, s[2:3]
	global_load_dword v183, v[2:3], off offset:512

; __device__ __forceinline__ float fexp2(float x) { return __builtin_amdgcn_exp2f(x); }
; __device__ __forceinline__ void diff_unit(LAS unsigned char* lds, const AP a, int l, int grp, int bl, int hd, int qb) {
;     ...
;             float mx = fmaxf(st0[0], st1[0]);
; #pragma unroll
;             for (int r = 1; r < 16; ++r) mx = fmaxf(mx, fmaxf(st0[r], st1[r]));
;             mx = xhalf_max(mx);
;             const float mn = fmaxf(m, basec + mx);
;             if (__builtin_amdgcn_ballot_w64(mn > m + RESCALE_THR) != 0ull) {
;                 const float alpha = fexp2(m - mn); m = mn; lsum *= alpha;
; #pragma unroll
;                 for (int i = 0; i < 4; ++i)
; #pragma unroll
;                     for (int r = 0; r < 16; ++r) o[i][r] *= alpha;
;             }
;             const float sh = m - basec;
;             if (__builtin_amdgcn_ballot_w64(sh != 0.f) != 0ull) {
; #pragma unroll
;                 for (int r = 0; r < 16; ++r) { st0[r] -= sh; st1[r] -= sh; }
;             }
.LBB0_154:
	s_add_i32 s0, s14, 1
	s_cmp_lg_u32 s14, 2
	s_cselect_b32 s19, s0, 0
	s_add_i32 s22, s22, 1
	v_readfirstlane_b32 s98, v210
	s_add_i32 s99, s12, 0x41
	s_cmp_le_i32 s99, s98
	s_cbranch_scc0 .Ldf_slow
	s_cmp_eq_u64 s[44:45], 0
	s_cbranch_scc1 .Ldf_slow
	s_cmp_eq_u64 s[4:5], 0
	s_cbranch_scc1 .Ldf_slow
	s_cmp_eq_u64 s[26:27], 0
	s_cbranch_scc1 .Ldf_slow
	s_lshl_b32 s6, s19, 2
	s_add_i32 s6, s6, 0x1a700
	v_mov_b32_e32 v252, s6
	s_mul_i32 s7, s19, 0x8c00
	ds_read_b32 v2, v252
	v_add_u32_e32 v252, s7, v226
	ds_read_b128 v[6:9], v252
	ds_read_b128 v[200:203], v252 offset:8704
	ds_read_b128 v[10:13], v252 offset:32
	ds_read_b128 v[242:245], v252 offset:8736
	ds_read_b128 v[234:237], v252 offset:64
	ds_read_b128 v[246:249], v252 offset:8768
	ds_read_b128 v[238:241], v252 offset:96
	s_mov_b32 s7, 0xefa18f08
	v_cmp_lt_f32_e32 vcc, s7, v233
	v_max3_f32 v0, v114, v115, v116
	v_max3_f32 v3, v130, v131, v132
	v_cndmask_b32_e32 v14, 0, v233, vcc
	v_max3_f32 v0, v0, v117, v118
	v_max3_f32 v3, v3, v133, v134
	v_max3_f32 v0, v0, v119, v120
	v_max3_f32 v3, v3, v135, v136
	v_max3_f32 v0, v0, v121, v122
	v_max3_f32 v3, v3, v137, v138
	v_max3_f32 v0, v0, v123, v124
	v_max3_f32 v3, v3, v139, v140
	v_max3_f32 v0, v0, v125, v126
	v_max3_f32 v3, v3, v141, v142
	v_max3_f32 v0, v0, v127, v128
	v_max3_f32 v3, v3, v143, v144
	v_max_f32_e32 v0, v0, v129
	v_max_f32_e32 v3, v3, v145
	v_max_f32_e32 v0, v0, v3
	v_mov_b32_e32 v3, v0
	s_nop 1
	v_permlane32_swap_b32_e32 v0, v3
	v_max_f32_e32 v0, v0, v3
	v_add_f32_e32 v0, v4, v0
	v_max_f32_e32 v0, v233, v0
	v_add_f32_e32 v3, 0x41000000, v233
	v_cmp_gt_f32_e32 vcc, v0, v3
	s_cbranch_vccz .Ldf_f_nr
	v_sub_f32_e32 v250, v233, v0
	v_exp_f32_e32 v250, v250
	v_mov_b32_e32 v233, v0
	v_pk_mul_f32 v[16:17], v[16:17], v[250:251] op_sel_hi:[1,0]
	v_pk_mul_f32 v[18:19], v[18:19], v[250:251] op_sel_hi:[1,0]
	v_pk_mul_f32 v[20:21], v[20:21], v[250:251] op_sel_hi:[1,0]
	v_pk_mul_f32 v[22:23], v[22:23], v[250:251] op_sel_hi:[1,0]
	v_pk_mul_f32 v[24:25], v[24:25], v[250:251] op_sel_hi:[1,0]
	v_pk_mul_f32 v[26:27], v[26:27], v[250:251] op_sel_hi:[1,0]
	v_pk_mul_f32 v[28:29], v[28:29], v[250:251] op_sel_hi:[1,0]
	v_pk_mul_f32 v[30:31], v[30:31], v[250:251] op_sel_hi:[1,0]
	v_pk_mul_f32 v[32:33], v[32:33], v[250:251] op_sel_hi:[1,0]
	v_pk_mul_f32 v[34:35], v[34:35], v[250:251] op_sel_hi:[1,0]
	v_pk_mul_f32 v[36:37], v[36:37], v[250:251] op_sel_hi:[1,0]
	v_pk_mul_f32 v[38:39], v[38:39], v[250:251] op_sel_hi:[1,0]
	v_pk_mul_f32 v[40:41], v[40:41], v[250:251] op_sel_hi:[1,0]
	v_pk_mul_f32 v[42:43], v[42:43], v[250:251] op_sel_hi:[1,0]
	v_pk_mul_f32 v[44:45], v[44:45], v[250:251] op_sel_hi:[1,0]
	v_pk_mul_f32 v[46:47], v[46:47], v[250:251] op_sel_hi:[1,0]
	v_pk_mul_f32 v[48:49], v[48:49], v[250:251] op_sel_hi:[1,0]
	v_pk_mul_f32 v[50:51], v[50:51], v[250:251] op_sel_hi:[1,0]
	v_pk_mul_f32 v[52:53], v[52:53], v[250:251] op_sel_hi:[1,0]
	v_pk_mul_f32 v[54:55], v[54:55], v[250:251] op_sel_hi:[1,0]
	v_pk_mul_f32 v[56:57], v[56:57], v[250:251] op_sel_hi:[1,0]
	v_pk_mul_f32 v[58:59], v[58:59], v[250:251] op_sel_hi:[1,0]
	v_pk_mul_f32 v[60:61], v[60:61], v[250:251] op_sel_hi:[1,0]
	v_pk_mul_f32 v[62:63], v[62:63], v[250:251] op_sel_hi:[1,0]
	v_pk_mul_f32 v[64:65], v[64:65], v[250:251] op_sel_hi:[1,0]
	v_pk_mul_f32 v[66:67], v[66:67], v[250:251] op_sel_hi:[1,0]
	v_pk_mul_f32 v[68:69], v[68:69], v[250:251] op_sel_hi:[1,0]
	v_pk_mul_f32 v[70:71], v[70:71], v[250:251] op_sel_hi:[1,0]
	v_pk_mul_f32 v[72:73], v[72:73], v[250:251] op_sel_hi:[1,0]
	v_pk_mul_f32 v[74:75], v[74:75], v[250:251] op_sel_hi:[1,0]
	v_pk_mul_f32 v[76:77], v[76:77], v[250:251] op_sel_hi:[1,0]
	v_pk_mul_f32 v[78:79], v[78:79], v[250:251] op_sel_hi:[1,0]
	v_mul_f32_e32 v80, v80, v250
.Ldf_f_nr:
	v_sub_f32_e32 v0, v233, v4
	v_cmp_neq_f32_e32 vcc, 0, v0
	s_cbranch_vccz .Ldf_f_nsh
	v_pk_add_f32 v[114:115], v[114:115], v[0:1] op_sel_hi:[1,0] neg_lo:[0,1] neg_hi:[0,1]
	v_pk_add_f32 v[116:117], v[116:117], v[0:1] op_sel_hi:[1,0] neg_lo:[0,1] neg_hi:[0,1]
	v_pk_add_f32 v[118:119], v[118:119], v[0:1] op_sel_hi:[1,0] neg_lo:[0,1] neg_hi:[0,1]
	v_pk_add_f32 v[120:121], v[120:121], v[0:1] op_sel_hi:[1,0] neg_lo:[0,1] neg_hi:[0,1]
	v_pk_add_f32 v[122:123], v[122:123], v[0:1] op_sel_hi:[1,0] neg_lo:[0,1] neg_hi:[0,1]
	v_pk_add_f32 v[124:125], v[124:125], v[0:1] op_sel_hi:[1,0] neg_lo:[0,1] neg_hi:[0,1]
	v_pk_add_f32 v[126:127], v[126:127], v[0:1] op_sel_hi:[1,0] neg_lo:[0,1] neg_hi:[0,1]
	v_pk_add_f32 v[128:129], v[128:129], v[0:1] op_sel_hi:[1,0] neg_lo:[0,1] neg_hi:[0,1]
	v_pk_add_f32 v[130:131], v[130:131], v[0:1] op_sel_hi:[1,0] neg_lo:[0,1] neg_hi:[0,1]
	v_pk_add_f32 v[132:133], v[132:133], v[0:1] op_sel_hi:[1,0] neg_lo:[0,1] neg_hi:[0,1]
	v_pk_add_f32 v[134:135], v[134:135], v[0:1] op_sel_hi:[1,0] neg_lo:[0,1] neg_hi:[0,1]
	v_pk_add_f32 v[136:137], v[136:137], v[0:1] op_sel_hi:[1,0] neg_lo:[0,1] neg_hi:[0,1]
	v_pk_add_f32 v[138:139], v[138:139], v[0:1] op_sel_hi:[1,0] neg_lo:[0,1] neg_hi:[0,1]
	v_pk_add_f32 v[140:141], v[140:141], v[0:1] op_sel_hi:[1,0] neg_lo:[0,1] neg_hi:[0,1]
	v_pk_add_f32 v[142:143], v[142:143], v[0:1] op_sel_hi:[1,0] neg_lo:[0,1] neg_hi:[0,1]
	v_pk_add_f32 v[144:145], v[144:145], v[0:1] op_sel_hi:[1,0] neg_lo:[0,1] neg_hi:[0,1]
; #define LAS __attribute__((address_space(3)))
; #define MFMA32(a, b, c) __builtin_amdgcn_mfma_f32_32x32x16_bf16((a), (b), (c), 0, 0, 0)
; __device__ __forceinline__ float fexp2(float x) { return __builtin_amdgcn_exp2f(x); }
; __device__ __forceinline__ void diff_unit(LAS unsigned char* lds, const AP a, int l, int grp, int bl, int hd, int qb) {
;     ...
;             float ls = 0.f;
; #pragma unroll
;             for (int r = 0; r < 16; ++r) { st0[r] = fexp2(st0[r]); st1[r] = fexp2(st1[r]); ls += st0[r] + st1[r]; }
;             lsum += ls;
;             const bf16x8 p0 = pack8(st0, 0), p1 = pack8(st0, 1), p2 = pack8(st1, 0), p3 = pack8(st1, 1);
; #pragma unroll
;             for (int dvb = 0; dvb < 4; ++dvb) {
;                 const bf16x8 v0 = *(const LAS bf16x8*)(bb + vrd + (dvb * 32 * VSTR) * 2);
;                 const bf16x8 v1 = *(const LAS bf16x8*)(bb + vrd + (dvb * 32 * VSTR + 16) * 2);
;                 o[dvb] = MFMA32(v0, p0, o[dvb]); o[dvb] = MFMA32(v1, p1, o[dvb]);
;                 if (a1c) {
;                     const bf16x8 v2 = *(const LAS bf16x8*)(bb + vrd + (dvb * 32 * VSTR + 32) * 2);
;                     const bf16x8 v3 = *(const LAS bf16x8*)(bb + vrd + (dvb * 32 * VSTR + 48) * 2);
;                     o[dvb] = MFMA32(v2, p2, o[dvb]); o[dvb] = MFMA32(v3, p3, o[dvb]); }
;             }
.Ldf_f_nsh:
	s_waitcnt lgkmcnt(7)
	v_sub_u32_e32 v2, v224, v2
	s_movk_i32 s7, 0x7f
	v_cmp_lt_i32_e32 vcc, s7, v2
	s_mov_b64 s[20:21], exec
	s_nop 0
	v_cndmask_b32_e32 v2, 0, v225, vcc
	s_mov_b64 s[16:17], vcc
	v_sub_f32_e32 v82, v2, v14
	v_mov_b32_e32 v83, v82
	v_mov_b64_e32 v[84:85], v[82:83]
	v_mov_b64_e32 v[86:87], v[82:83]
	v_mov_b64_e32 v[88:89], v[82:83]
	v_mov_b64_e32 v[90:91], v[82:83]
	v_mov_b64_e32 v[92:93], v[82:83]
	v_mov_b64_e32 v[94:95], v[82:83]
	v_mov_b64_e32 v[96:97], v[82:83]
	v_mov_b64_e32 v[98:99], v[82:83]
	v_mov_b64_e32 v[100:101], v[82:83]
	v_mov_b64_e32 v[102:103], v[82:83]
	v_mov_b64_e32 v[104:105], v[82:83]
	v_mov_b64_e32 v[106:107], v[82:83]
	v_mov_b64_e32 v[108:109], v[82:83]
	v_mov_b64_e32 v[110:111], v[82:83]
	v_mov_b64_e32 v[112:113], v[82:83]
	s_waitcnt lgkmcnt(6)
	v_mfma_f32_32x32x16_bf16 v[82:97], v[6:9], v[146:149], v[82:97]
	ds_read_b128 v[6:9], v252 offset:8800
	s_mul_i32 s0, s14, 0x8c00
	v_exp_f32_e32 v114, v114
	v_exp_f32_e32 v115, v115
	v_exp_f32_e32 v116, v116
	s_waitcnt lgkmcnt(6)
	v_mfma_f32_32x32x16_bf16 v[98:113], v[200:203], v[146:149], v[98:113]
	v_add_u32_e32 v252, s0, v228
	ds_read_b128 v[200:203], v252 offset:17408
	v_exp_f32_e32 v117, v117
	v_exp_f32_e32 v118, v118
	v_exp_f32_e32 v119, v119
	s_waitcnt lgkmcnt(6)
	v_mfma_f32_32x32x16_bf16 v[82:97], v[10:13], v[150:153], v[82:97]
	v_exp_f32_e32 v120, v120
	v_exp_f32_e32 v121, v121
	v_cvt_pk_bf16_f32 v2, v114, v115
	s_waitcnt lgkmcnt(5)
	v_mfma_f32_32x32x16_bf16 v[98:113], v[242:245], v[150:153], v[98:113]
	ds_read_b128 v[242:245], v252 offset:22016
	v_cvt_pk_bf16_f32 v3, v116, v117
	v_cvt_pk_bf16_f32 v4, v118, v119
	v_cvt_pk_bf16_f32 v5, v120, v121
	s_waitcnt lgkmcnt(5)
	v_mfma_f32_32x32x16_bf16 v[82:97], v[234:237], v[154:157], v[82:97]
	ds_read_b128 v[234:237], v252 offset:26624
	v_pk_add_f32 v[250:251], v[114:115], v[116:117]
	v_exp_f32_e32 v122, v122
	v_exp_f32_e32 v123, v123
	s_waitcnt lgkmcnt(5)
	v_mfma_f32_32x32x16_bf16 v[98:113], v[246:249], v[154:157], v[98:113]
	ds_read_b128 v[246:249], v252 offset:31232
	v_pk_add_f32 v[250:251], v[250:251], v[118:119]
	v_exp_f32_e32 v124, v124
	v_exp_f32_e32 v125, v125
	s_waitcnt lgkmcnt(5)
	v_mfma_f32_32x32x16_bf16 v[82:97], v[238:241], v[158:161], v[82:97]
	v_pk_add_f32 v[250:251], v[250:251], v[120:121]
	v_exp_f32_e32 v126, v126
	v_exp_f32_e32 v127, v127
	s_waitcnt lgkmcnt(4)
	v_mfma_f32_32x32x16_bf16 v[98:113], v[6:9], v[158:161], v[98:113]
	v_exp_f32_e32 v128, v128
	v_exp_f32_e32 v129, v129
	s_waitcnt lgkmcnt(3)
	v_mfma_f32_32x32x16_bf16 v[48:63], v[200:203], v[2:5], v[48:63]
	ds_read_b128 v[200:203], v252 offset:17440
	v_cvt_pk_bf16_f32 v114, v122, v123
	v_cvt_pk_bf16_f32 v115, v124, v125
	s_waitcnt lgkmcnt(3)
	v_mfma_f32_32x32x16_bf16 v[32:47], v[242:245], v[2:5], v[32:47]
	ds_read_b128 v[242:245], v252 offset:22048
	v_cvt_pk_bf16_f32 v116, v126, v127
	v_cvt_pk_bf16_f32 v117, v128, v129
	s_waitcnt lgkmcnt(3)
	v_mfma_f32_32x32x16_bf16 v[16:31], v[234:237], v[2:5], v[16:31]
	ds_read_b128 v[234:237], v252 offset:26656
	v_exp_f32_e32 v130, v130
	v_exp_f32_e32 v131, v131
	v_exp_f32_e32 v132, v132
	s_waitcnt lgkmcnt(3)
	v_mfma_f32_32x32x16_bf16 v[64:79], v[246:249], v[2:5], v[64:79]
	ds_read_b128 v[246:249], v252 offset:31264
	v_exp_f32_e32 v133, v133
	v_exp_f32_e32 v134, v134
	v_pk_add_f32 v[250:251], v[250:251], v[122:123]
	s_waitcnt lgkmcnt(3)
	v_mfma_f32_32x32x16_bf16 v[48:63], v[200:203], v[114:117], v[48:63]
	ds_read_b128 v[200:203], v252 offset:17472
	v_exp_f32_e32 v135, v135
	v_exp_f32_e32 v136, v136
	v_exp_f32_e32 v137, v137
	s_waitcnt lgkmcnt(3)
	v_mfma_f32_32x32x16_bf16 v[32:47], v[242:245], v[114:117], v[32:47]
	ds_read_b128 v[242:245], v252 offset:22080
	v_exp_f32_e32 v138, v138
	v_exp_f32_e32 v139, v139
	v_pk_add_f32 v[250:251], v[250:251], v[124:125]
	s_waitcnt lgkmcnt(3)
	v_mfma_f32_32x32x16_bf16 v[16:31], v[234:237], v[114:117], v[16:31]
	ds_read_b128 v[234:237], v252 offset:26688
	v_exp_f32_e32 v140, v140
	v_exp_f32_e32 v141, v141
	v_pk_add_f32 v[250:251], v[250:251], v[126:127]
	s_waitcnt lgkmcnt(3)
	v_mfma_f32_32x32x16_bf16 v[64:79], v[246:249], v[114:117], v[64:79]
	ds_read_b128 v[246:249], v252 offset:31296
	v_cvt_pk_bf16_f32 v10, v130, v131
	v_cvt_pk_bf16_f32 v11, v132, v133
	v_cvt_pk_bf16_f32 v12, v134, v135
	v_cvt_pk_bf16_f32 v13, v136, v137
	v_exp_f32_e32 v142, v142
	v_exp_f32_e32 v143, v143
	s_waitcnt lgkmcnt(3)
	v_mfma_f32_32x32x16_bf16 v[48:63], v[200:203], v[10:13], v[48:63]
	ds_read_b128 v[200:203], v252 offset:17504
	v_exp_f32_e32 v144, v144
	v_exp_f32_e32 v145, v145
	v_pk_add_f32 v[250:251], v[250:251], v[128:129]
	s_waitcnt lgkmcnt(3)
	v_mfma_f32_32x32x16_bf16 v[32:47], v[242:245], v[10:13], v[32:47]
	ds_read_b128 v[242:245], v252 offset:22112
	v_cvt_pk_bf16_f32 v6, v138, v139
	v_cvt_pk_bf16_f32 v7, v140, v141
	v_cvt_pk_bf16_f32 v8, v142, v143
	s_waitcnt lgkmcnt(3)
	v_mfma_f32_32x32x16_bf16 v[16:31], v[234:237], v[10:13], v[16:31]
	ds_read_b128 v[234:237], v252 offset:26720
	v_cvt_pk_bf16_f32 v9, v144, v145
	v_pk_add_f32 v[250:251], v[250:251], v[130:131]
	v_pk_add_f32 v[250:251], v[250:251], v[132:133]
	s_waitcnt lgkmcnt(3)
	v_mfma_f32_32x32x16_bf16 v[64:79], v[246:249], v[10:13], v[64:79]
	ds_read_b128 v[246:249], v252 offset:31328
	v_pk_add_f32 v[250:251], v[250:251], v[134:135]
	v_pk_add_f32 v[250:251], v[250:251], v[136:137]
	v_pk_add_f32 v[250:251], v[250:251], v[138:139]
	s_waitcnt lgkmcnt(3)
	v_mfma_f32_32x32x16_bf16 v[48:63], v[200:203], v[6:9], v[48:63]
	v_pk_add_f32 v[250:251], v[250:251], v[140:141]
	v_pk_add_f32 v[250:251], v[250:251], v[142:143]
	v_pk_add_f32 v[250:251], v[250:251], v[144:145]
	s_waitcnt lgkmcnt(2)
	v_mfma_f32_32x32x16_bf16 v[32:47], v[242:245], v[6:9], v[32:47]
	v_add_f32_e32 v250, v250, v251
	v_add_f32_e32 v80, v80, v250
	s_waitcnt lgkmcnt(1)
	v_mfma_f32_32x32x16_bf16 v[16:31], v[234:237], v[6:9], v[16:31]
	s_waitcnt lgkmcnt(0)
	v_mfma_f32_32x32x16_bf16 v[64:79], v[246:249], v[6:9], v[64:79]
	s_branch .LBB0_177
; __device__ __forceinline__ void diff_unit(LAS unsigned char* lds, const AP a, int l, int grp, int bl, int hd, int qb) {
;     ...
;         if (kt + 1 < ntiles && k0 + 64 <= q0 + 31) { farn = (qmin - posk[192 + bnx] >= 128); a1n = (k0 + 96 <= q0 + 31); DF_QK(lds + bnx * BUF, sn0, sn1, basen, a1n, farn); }
.Ldf_slow:
	s_cmp_lt_i32 s22, s15
	s_cselect_b64 s[0:1], -1, 0
	s_add_i32 s6, s12, 33
	v_cmp_le_i32_e32 vcc, s6, v210
	s_and_b64 s[6:7], s[0:1], vcc
	v_mov_b32_e32 v14, v4
	s_and_saveexec_b64 s[0:1], s[6:7]
	s_cbranch_execz .LBB0_159
	s_lshl_b32 s6, s19, 2
	s_add_i32 s6, s6, 0
	s_add_i32 s6, s6, 0x1a700
	v_mov_b32_e32 v0, s6
	s_mul_i32 s7, s19, 0x8c00
	ds_read_b32 v2, v0
	v_add_u32_e32 v0, s7, v226
	ds_read_b128 v[6:9], v0
	s_mov_b32 s7, 0xefa18f08
	v_cmp_lt_f32_e32 vcc, s7, v233
	s_waitcnt lgkmcnt(0)
	v_sub_u32_e32 v2, v224, v2
	s_movk_i32 s7, 0x7f
	v_cndmask_b32_e32 v14, 0, v233, vcc
	v_cmp_lt_i32_e32 vcc, s7, v2
	s_add_i32 s6, s12, 0x41
	v_cmp_le_i32_e64 s[42:43], s6, v210
	v_cndmask_b32_e32 v2, 0, v225, vcc
	v_sub_f32_e32 v82, v2, v14
	v_mov_b32_e32 v83, v82
	v_mov_b32_e32 v84, v82
	v_mov_b32_e32 v85, v82
	v_mov_b32_e32 v86, v82
	v_mov_b32_e32 v87, v82
	v_mov_b32_e32 v88, v82
	v_mov_b32_e32 v89, v82
	v_mov_b32_e32 v90, v82
	v_mov_b32_e32 v91, v82
	v_mov_b32_e32 v92, v82
	v_mov_b32_e32 v93, v82
	v_mov_b32_e32 v94, v82
	v_mov_b32_e32 v95, v82
	v_mov_b32_e32 v96, v82
	v_mov_b32_e32 v97, v82
	v_cndmask_b32_e64 v98, v197, v82, s[42:43]
	v_mov_b32_e32 v99, v98
	v_mfma_f32_32x32x16_bf16 v[82:97], v[6:9], v[146:149], v[82:97]
	ds_read_b128 v[6:9], v0 offset:32
	v_mov_b32_e32 v100, v98
	v_mov_b32_e32 v101, v98
	v_mov_b32_e32 v102, v98
	v_mov_b32_e32 v103, v98
	v_mov_b32_e32 v104, v98
	v_mov_b32_e32 v105, v98
	s_waitcnt lgkmcnt(0)
	v_mfma_f32_32x32x16_bf16 v[82:97], v[6:9], v[150:153], v[82:97]
	ds_read_b128 v[6:9], v0 offset:64
	v_mov_b32_e32 v106, v98
	v_mov_b32_e32 v107, v98
	v_mov_b32_e32 v108, v98
	v_mov_b32_e32 v109, v98
	v_mov_b32_e32 v110, v98
	v_mov_b32_e32 v111, v98
	s_waitcnt lgkmcnt(0)
	v_mfma_f32_32x32x16_bf16 v[82:97], v[6:9], v[154:157], v[82:97]
	ds_read_b128 v[6:9], v0 offset:96
	v_mov_b32_e32 v112, v98
	v_mov_b32_e32 v113, v98
	s_mov_b64 s[6:7], 0
	s_waitcnt lgkmcnt(0)
	v_mfma_f32_32x32x16_bf16 v[82:97], v[6:9], v[158:161], v[82:97]
	s_and_saveexec_b64 s[24:25], s[42:43]
	s_cbranch_execz .LBB0_157
	ds_read_b128 v[6:9], v0 offset:8704
	s_mov_b64 s[6:7], exec
	s_waitcnt lgkmcnt(0)
	v_mfma_f32_32x32x16_bf16 v[98:113], v[6:9], v[146:149], v[98:113]
	ds_read_b128 v[6:9], v0 offset:8736
	s_waitcnt lgkmcnt(0)
	v_mfma_f32_32x32x16_bf16 v[98:113], v[6:9], v[150:153], v[98:113]
	ds_read_b128 v[6:9], v0 offset:8768
	s_waitcnt lgkmcnt(0)
	v_mfma_f32_32x32x16_bf16 v[98:113], v[6:9], v[154:157], v[98:113]
	ds_read_b128 v[6:9], v0 offset:8800
	s_waitcnt lgkmcnt(0)
	v_mfma_f32_32x32x16_bf16 v[98:113], v[6:9], v[158:161], v[98:113]

; __global__ void __launch_bounds__(NTHREADS, 2) mega(Args a_unused) {
	.amdhsa_kernel _Z4mega4Args
		.amdhsa_group_segment_fixed_size 0
		.amdhsa_private_segment_fixed_size 0
		.amdhsa_kernarg_size 544
		.amdhsa_user_sgpr_count 2
		.amdhsa_user_sgpr_dispatch_ptr 0
		.amdhsa_user_sgpr_queue_ptr 0
		.amdhsa_user_sgpr_kernarg_segment_ptr 1
		.amdhsa_user_sgpr_dispatch_id 0
		.amdhsa_user_sgpr_kernarg_preload_length 0
		.amdhsa_user_sgpr_kernarg_preload_offset 0
		.amdhsa_user_sgpr_private_segment_size 0
		.amdhsa_uses_dynamic_stack 0
		.amdhsa_enable_private_segment 0
		.amdhsa_system_sgpr_workgroup_id_x 1
		.amdhsa_system_sgpr_workgroup_id_y 0
		.amdhsa_system_sgpr_workgroup_id_z 0
		.amdhsa_system_sgpr_workgroup_info 0
		.amdhsa_system_vgpr_workitem_id 2
		.amdhsa_next_free_vgpr 256
		.amdhsa_next_free_sgpr 102
		.amdhsa_accum_offset 256
		.amdhsa_reserve_vcc 1
		.amdhsa_float_round_mode_32 0
		.amdhsa_float_round_mode_16_64 0
		.amdhsa_float_denorm_mode_32 3
		.amdhsa_float_denorm_mode_16_64 3
		.amdhsa_dx10_clamp 1
		.amdhsa_ieee_mode 1
		.amdhsa_fp16_overflow 0
		.amdhsa_tg_split 0
		.amdhsa_exception_fp_ieee_invalid_op 0
		.amdhsa_exception_fp_denorm_src 0
		.amdhsa_exception_fp_ieee_div_zero 0
		.amdhsa_exception_fp_ieee_overflow 0
		.amdhsa_exception_fp_ieee_underflow 0
		.amdhsa_exception_fp_ieee_inexact 0
		.amdhsa_exception_int_div_zero 0
	.end_amdhsa_kernel

; __global__ void __launch_bounds__(NTHREADS, 2) mega(Args a_unused) {
.Lfunc_end0:
	.size	_Z4mega4Args, .Lfunc_end0-_Z4mega4Args
	.set _Z4mega4Args.num_vgpr, 256
	.set _Z4mega4Args.num_agpr, 0
	.set _Z4mega4Args.numbered_sgpr, 102
	.set _Z4mega4Args.num_named_barrier, 0
	.set _Z4mega4Args.private_seg_size, 0
	.set _Z4mega4Args.uses_vcc, 1
	.set _Z4mega4Args.uses_flat_scratch, 0
	.set _Z4mega4Args.has_dyn_sized_stack, 0
	.set _Z4mega4Args.has_recursion, 0
	.set _Z4mega4Args.has_indirect_call, 0

; __global__ void __launch_bounds__(NTHREADS, 2) mega(Args a_unused) {
amdhsa.kernels:
  - .agpr_count:     0
    .args:
      - .offset:         0
        .size:           288
        .value_kind:     by_value
      - .offset:         288
        .size:           4
        .value_kind:     hidden_block_count_x
      - .offset:         292
        .size:           4
        .value_kind:     hidden_block_count_y
      - .offset:         296
        .size:           4
        .value_kind:     hidden_block_count_z
      - .offset:         300
        .size:           2
        .value_kind:     hidden_group_size_x
      - .offset:         302
        .size:           2
        .value_kind:     hidden_group_size_y
      - .offset:         304
        .size:           2
        .value_kind:     hidden_group_size_z
      - .offset:         306
        .size:           2
        .value_kind:     hidden_remainder_x
      - .offset:         308
        .size:           2
        .value_kind:     hidden_remainder_y
      - .offset:         310
        .size:           2
        .value_kind:     hidden_remainder_z
      - .offset:         328
        .size:           8
        .value_kind:     hidden_global_offset_x
      - .offset:         336
        .size:           8
        .value_kind:     hidden_global_offset_y
      - .offset:         344
        .size:           8
        .value_kind:     hidden_global_offset_z
      - .offset:         352
        .size:           2
        .value_kind:     hidden_grid_dims
      - .offset:         376
        .size:           8
        .value_kind:     hidden_multigrid_sync_arg
      - .offset:         408
        .size:           4
        .value_kind:     hidden_dynamic_lds_size
    .group_segment_fixed_size: 0
    .kernarg_segment_align: 8
    .kernarg_segment_size: 544
    .language:       OpenCL C
    .language_version:
      - 2
      - 0
    .max_flat_workgroup_size: 512
    .name:           _Z4mega4Args
    .private_segment_fixed_size: 0
    .sgpr_count:     108
    .sgpr_spill_count: 192
    .symbol:         _Z4mega4Args.kd
    .uniform_work_group_size: 1
    .uses_dynamic_stack: false
    .vgpr_count:     256
    .vgpr_spill_count: 0
    .wavefront_size: 64
